# merge with 16-token units (2 tokens per wave), attention queue ticket fetched asynchronously, scan WGs skip the empty attention queue, prep un-serialised
# speedup vs baseline: 1.1490x; 1.0006x over previous
.LBB0_1130:
	s_add_u32 s10, s88, 0x3700
	s_addc_u32 s11, s89, 0
	s_and_b32 s18, s33, 7
	s_mov_b32 s85, 0
	v_lshrrev_b32_e32 v142, 8, v141
	v_mov_b32_e32 v130, -1
	v_mov_b32_e32 v144, 0
	v_mov_b32_e32 v143, s18
	s_and_saveexec_b64 s[12:13], s[92:93]
	s_cbranch_execz .LBB0_1148
	s_waitcnt vmcnt(15)
	v_mov_b32_e32 v1, 0
	v_mov_b32_e32 v2, -1
	s_mov_b64 s[16:17], 0
	v_mov_b32_e32 v143, s18
	v_mov_b32_e32 v3, 1
	s_movk_i32 s23, 0x180
	v_mov_b32_e32 v144, 0
	s_branch .LBB0_1134

.LBB0_1148:
	s_or_b64 exec, exec, s[12:13]
	s_add_i32 s23, 0, 0x25e08
	s_waitcnt vmcnt(15)
	v_mov_b32_e32 v1, s23
	s_waitcnt lgkmcnt(0)
	s_barrier
	ds_read_b32 v1, v1
	v_mul_u32_u24_e32 v0, 0x12000, v142
	v_mbcnt_lo_u32_b32 v139, -1, 0
	s_waitcnt lgkmcnt(0)
	v_cmp_gt_i32_e32 vcc, 0, v1
	v_readfirstlane_b32 s84, v1
	s_cbranch_vccnz .LBB0_1169
	v_add_u32_e32 v1, 0, v0
	v_bfe_u32 v145, v141, 3, 5
	v_bfe_u32 v0, v141, 1, 7
	s_movk_i32 s24, 0x60
	v_and_b32_e32 v2, 6, v162
	v_and_or_b32 v150, v0, s24, v140
	v_and_b32_e32 v68, 24, v0
	v_mul_u32_u24_e32 v0, 0x48, v145
	s_waitcnt vmcnt(13)
	v_lshlrev_b32_e32 v4, 4, v2
	v_lshlrev_b32_e32 v0, 1, v0
	v_or_b32_e32 v5, 16, v4
	v_add3_u32 v151, v1, v128, v0
	v_add3_u32 v152, v1, v0, v128
	v_or_b32_e32 v0, v5, v140
	v_add_u32_e32 v6, 32, v4
	v_mul_u32_u24_e32 v71, 0x90, v0
	v_or_b32_e32 v0, v6, v140
	v_add_u32_e32 v7, 48, v4
	v_mul_u32_u24_e32 v72, 0x90, v0
	v_or_b32_e32 v0, v7, v140
	v_add_u32_e32 v8, 64, v4
	v_mul_u32_u24_e32 v73, 0x90, v0
	v_or_b32_e32 v0, v8, v140
	v_add_u32_e32 v9, 0x50, v4
	v_mul_u32_u24_e32 v74, 0x90, v0
	v_or_b32_e32 v0, v9, v140
	v_add_u32_e32 v10, 0x60, v4
	v_mul_u32_u24_e32 v75, 0x90, v0
	v_or_b32_e32 v0, v10, v140
	v_add_u32_e32 v11, 0x70, v4
	s_mul_hi_u32 s12, s84, 0xaaaaaaab
	v_mul_u32_u24_e32 v76, 0x90, v0
	v_or_b32_e32 v0, v11, v140
	v_or_b32_e32 v12, 0x80, v4
	s_lshr_b32 s12, s12, 8
	v_mul_u32_u24_e32 v77, 0x90, v0
	v_or_b32_e32 v0, v12, v140
	s_mul_i32 s13, s12, 0x180
	v_mul_u32_u24_e32 v78, 0x90, v0
	v_lshlrev_b32_e32 v0, 2, v171
	s_sub_i32 s13, s84, s13
	v_or_b32_e32 v79, v0, v137
	s_lshl_b32 s16, s13, 1
	v_or_b32_e32 v155, v4, v140
	v_or_b32_e32 v4, v79, v4
	v_or_b32_e32 v105, 1, v2
	s_and_b32 s17, s16, 0xfffe
	v_mul_u32_u24_e32 v80, 0x90, v4
	v_or_b32_e32 v4, v5, v79
	v_lshlrev_b32_e32 v106, 4, v105
	s_mulk_i32 s17, 0x2aab
	s_mul_i32 s13, s13, 0xaaab
	v_mul_u32_u24_e32 v81, 0x90, v4
	v_or_b32_e32 v4, v6, v79
	v_add_u32_e32 v108, 16, v106
	s_lshr_b32 s17, s17, 20
	s_lshr_b32 s13, s13, 18
	v_cmp_eq_u32_e64 s[50:51], 6, v2
	v_cmp_gt_u32_e64 s[52:53], 5, v2
	v_cmp_gt_u32_e64 s[54:55], 4, v2
	v_cmp_gt_u32_e64 s[56:57], 3, v2
	v_cmp_eq_u32_e64 s[58:59], 0, v2
	v_mul_u32_u24_e32 v82, 0x90, v4
	v_or_b32_e32 v4, v7, v79
	v_or_b32_e32 v2, v108, v140
	v_add_u32_e32 v110, 32, v106
	s_mulk_i32 s17, 0x60
	s_and_b32 s13, s13, 0x3ff8
	v_mul_u32_u24_e32 v83, 0x90, v4
	v_or_b32_e32 v4, v8, v79
	v_mul_u32_u24_e32 v109, 0x90, v2
	v_or_b32_e32 v2, v110, v140
	v_add_u32_e32 v112, 48, v106
	s_sub_i32 s16, s16, s17
	s_add_i32 s12, s12, s13
	v_mul_u32_u24_e32 v100, 0x90, v4
	v_or_b32_e32 v4, v9, v79
	v_mul_u32_u24_e32 v111, 0x90, v2
	v_or_b32_e32 v2, v112, v140
	v_add_u32_e32 v114, 64, v106
	s_and_b32 s16, s16, 0xfffe
	s_mulk_i32 s12, 0x60
	v_mul_u32_u24_e32 v101, 0x90, v4
	v_or_b32_e32 v4, v10, v79
	v_mul_u32_u24_e32 v113, 0x90, v2
	v_or_b32_e32 v2, v114, v140
	s_add_i32 s12, s12, s16
	v_mul_u32_u24_e32 v102, 0x90, v4
	v_or_b32_e32 v4, v11, v79
	v_mul_u32_u24_e32 v115, 0x90, v2
	s_mov_b32 s25, 0xaaaaaaab
	v_add_u32_e32 v2, s12, v142
	v_mul_u32_u24_e32 v103, 0x90, v4
	v_or_b32_e32 v4, v12, v79
	v_mul_hi_u32 v6, v2, s25
	v_mul_u32_u24_e32 v104, 0x90, v4
	v_lshlrev_b32_e32 v4, 3, v6
	v_lshrrev_b32_e32 v7, 6, v6
	v_and_b32_e32 v8, 0x7ffff000, v4
	s_movk_i32 s26, 0x2100
	v_mov_b64_e32 v[4:5], s[78:79]
	v_mad_u64_u32 v[60:61], s[12:13], v8, s26, v[4:5]
	v_mul_lo_u32 v4, v7, s24
	v_sub_u32_e32 v2, v2, v4
	v_and_b32_e32 v4, 31, v2
	v_lshrrev_b32_e32 v2, 4, v2
	v_and_b32_e32 v62, 6, v2
	s_waitcnt vmcnt(6)
	v_lshrrev_b32_e32 v36, v62, v4
	v_lshlrev_b32_e32 v8, 7, v36
	v_or_b32_e32 v2, v8, v150
	v_bfe_u32 v63, v4, 0, v62
	v_lshl_add_u32 v2, v2, v62, v63
	v_mad_u64_u32 v[4:5], s[12:13], v2, s26, v[60:61]
	v_lshlrev_b32_e32 v2, 1, v6
	v_mov_b32_e32 v3, 0
	v_and_b32_e32 v2, 0x380, v2
	v_lshl_add_u64 v[4:5], v[4:5], 0, v[2:3]
	v_lshlrev_b32_e32 v6, 1, v68
	v_mov_b32_e32 v7, v3
	v_lshl_add_u64 v[4:5], v[4:5], 0, v[6:7]
	v_add_u32_e32 v6, 4, v62
	s_mov_b64 s[12:13], 0x1080
	v_lshlrev_b64 v[6:7], v6, s[12:13]
	v_or_b32_e32 v149, 0xe0, v145
	v_lshl_add_u64 v[6:7], v[6:7], 1, v[4:5]
	v_add_u32_e32 v37, 0xffffff80, v8
	v_or_b32_e32 v13, 1, v0
	global_load_dwordx4 v[84:87], v[6:7], off offset:3392
	global_load_dwordx4 v[88:91], v[6:7], off offset:3328
	global_load_dwordx4 v[92:95], v[4:5], off offset:3392
	global_load_dwordx4 v[96:99], v[4:5], off offset:3328
	v_add_u32_e32 v4, v37, v149
	v_or_b32_e32 v148, 0xc0, v145
	v_cmp_lt_u32_e64 s[40:41], v13, v140
	v_or_b32_e32 v13, 2, v0
	v_lshl_add_u32 v4, v4, v62, v63
	v_cmp_lt_u32_e64 s[42:43], v13, v140
	v_cmp_gt_u32_e64 s[44:45], v13, v140
	v_or_b32_e32 v13, 3, v0
	v_mad_u64_u32 v[4:5], s[16:17], v4, s26, v[60:61]
	v_add_u32_e32 v12, v37, v148
	v_or_b32_e32 v147, 0xa0, v145
	v_cmp_lt_u32_e64 s[46:47], v13, v140
	v_cmp_gt_u32_e64 s[48:49], v13, v140
	v_and_b32_e32 v13, 12, v172
	v_lshl_add_u64 v[4:5], v[4:5], 0, v[2:3]
	v_mov_b32_e32 v129, v3
	v_lshl_add_u32 v12, v12, v62, v63
	v_add_u32_e32 v69, v1, v173
	v_lshl_add_u32 v1, v13, 1, v1
	v_lshl_add_u64 v[4:5], v[4:5], 0, v[128:129]
	s_movk_i32 s27, 0x1000
	v_mad_u64_u32 v[12:13], s[16:17], v12, s26, v[60:61]
	v_add_u32_e32 v20, v37, v147
	v_or_b32_e32 v146, 0x80, v145
	v_add_co_u32_e32 v8, vcc, s27, v4
	v_lshl_add_u64 v[12:13], v[12:13], 0, v[2:3]
	v_lshl_add_u32 v20, v20, v62, v63
	v_addc_co_u32_e32 v9, vcc, 0, v5, vcc
	v_lshl_add_u64 v[12:13], v[12:13], 0, v[128:129]
	v_mad_u64_u32 v[20:21], s[16:17], v20, s26, v[60:61]
	v_add_u32_e32 v28, v37, v146
	v_add_co_u32_e32 v16, vcc, s27, v12
	v_lshl_add_u64 v[20:21], v[20:21], 0, v[2:3]
	v_lshl_add_u32 v28, v28, v62, v63
	v_addc_co_u32_e32 v17, vcc, 0, v13, vcc
	v_lshl_add_u64 v[20:21], v[20:21], 0, v[128:129]
	v_mad_u64_u32 v[28:29], s[16:17], v28, s26, v[60:61]
	v_add_co_u32_e32 v24, vcc, s27, v20
	v_lshl_add_u64 v[28:29], v[28:29], 0, v[2:3]
	s_nop 0
	v_addc_co_u32_e32 v25, vcc, 0, v21, vcc
	v_lshl_add_u64 v[28:29], v[28:29], 0, v[128:129]
	v_add_co_u32_e32 v32, vcc, s27, v28
	v_or_b32_e32 v64, v37, v145
	s_nop 0
	v_addc_co_u32_e32 v33, vcc, 0, v29, vcc
	v_or_b32_e32 v37, 0x60, v64
	v_cmp_eq_u32_e32 vcc, 0, v36
	v_or_b32_e32 v44, 64, v64
	v_or_b32_e32 v52, 32, v64
	v_cndmask_b32_e64 v36, v37, 0, vcc
	v_lshl_add_u32 v36, v36, v62, v63
	v_mad_i64_i32 v[36:37], s[16:17], v36, s26, v[60:61]
	v_cndmask_b32_e64 v44, v44, 0, vcc
	v_lshl_add_u64 v[36:37], v[36:37], 0, v[2:3]
	v_lshl_add_u32 v44, v44, v62, v63
	v_lshl_add_u64 v[36:37], v[36:37], 0, v[128:129]
	v_mad_i64_i32 v[44:45], s[16:17], v44, s26, v[60:61]
	v_cndmask_b32_e64 v52, v52, 0, vcc
	v_cndmask_b32_e64 v64, v64, 0, vcc
	v_add_co_u32_e64 v40, s[62:63], s27, v36
	v_lshl_add_u64 v[44:45], v[44:45], 0, v[2:3]
	v_lshl_add_u32 v52, v52, v62, v63
	v_lshl_add_u32 v62, v64, v62, v63
	v_addc_co_u32_e64 v41, s[62:63], 0, v37, s[62:63]
	v_lshl_add_u64 v[44:45], v[44:45], 0, v[128:129]
	v_mad_i64_i32 v[52:53], s[16:17], v52, s26, v[60:61]
	v_mad_i64_i32 v[60:61], s[16:17], v62, s26, v[60:61]
	v_add_co_u32_e64 v48, s[62:63], s27, v44
	v_lshl_add_u64 v[52:53], v[52:53], 0, v[2:3]
	v_lshl_add_u64 v[60:61], v[60:61], 0, v[2:3]
	v_addc_co_u32_e64 v49, s[62:63], 0, v45, s[62:63]
	v_lshl_add_u64 v[52:53], v[52:53], 0, v[128:129]
	v_lshl_add_u64 v[60:61], v[60:61], 0, v[128:129]
	v_add_co_u32_e64 v56, s[62:63], s27, v52
	v_add_co_u32_e32 v64, vcc, s27, v60
	s_nop 0
	v_addc_co_u32_e64 v57, s[62:63], 0, v53, s[62:63]
	v_addc_co_u32_e32 v65, vcc, 0, v61, vcc
	global_load_dwordx4 v[4:7], v[8:9], off offset:1280
	s_nop 0
	global_load_dwordx4 v[8:11], v[8:9], off offset:256
	s_nop 0
	global_load_dwordx4 v[12:15], v[16:17], off offset:1280
	s_nop 0
	global_load_dwordx4 v[16:19], v[16:17], off offset:256
	s_nop 0
	global_load_dwordx4 v[20:23], v[24:25], off offset:1280
	s_nop 0
	global_load_dwordx4 v[24:27], v[24:25], off offset:256
	s_nop 0
	global_load_dwordx4 v[28:31], v[32:33], off offset:1280
	s_nop 0
	global_load_dwordx4 v[32:35], v[32:33], off offset:256
	s_nop 0
	global_load_dwordx4 v[36:39], v[40:41], off offset:1280
	s_nop 0
	global_load_dwordx4 v[40:43], v[40:41], off offset:256
	s_nop 0
	global_load_dwordx4 v[44:47], v[48:49], off offset:1280
	s_nop 0
	global_load_dwordx4 v[48:51], v[48:49], off offset:256
	s_nop 0
	global_load_dwordx4 v[52:55], v[56:57], off offset:1280
	s_nop 0
	global_load_dwordx4 v[56:59], v[56:57], off offset:256
	s_nop 0
	global_load_dwordx4 v[60:63], v[64:65], off offset:1280
	s_nop 0
	global_load_dwordx4 v[64:67], v[64:65], off offset:256
	v_add_u32_e32 v2, 0x50, v106
	v_add_u32_e32 v117, 0x60, v106
	v_add_u32_e32 v119, 0x70, v106
	v_or_b32_e32 v121, 0x80, v106
	v_or_b32_e32 v137, v106, v140
	v_or_b32_e32 v116, v2, v140
	v_or_b32_e32 v118, v117, v140
	v_or_b32_e32 v120, v119, v140
	v_or_b32_e32 v122, v121, v140
	v_cmp_gt_u32_e64 s[62:63], 5, v105
	v_cmp_gt_u32_e64 s[64:65], 3, v105
	v_or_b32_e32 v105, v106, v79
	v_or_b32_e32 v106, v108, v79
	v_or_b32_e32 v108, v110, v79
	v_or_b32_e32 v110, v112, v79
	v_or_b32_e32 v112, v114, v79
	v_or_b32_e32 v2, v2, v79
	v_or_b32_e32 v114, v117, v79
	v_or_b32_e32 v117, v119, v79
	v_or_b32_e32 v79, v121, v79
	v_mul_u32_u24_e32 v70, 0x90, v155
	v_mul_u32_u24_e32 v107, 0x90, v137
	v_mul_u32_u24_e32 v116, 0x90, v116
	v_mul_u32_u24_e32 v118, 0x90, v118
	v_mul_u32_u24_e32 v120, 0x90, v120
	v_mul_u32_u24_e32 v122, 0x90, v122
	v_mul_u32_u24_e32 v105, 0x90, v105
	v_mul_u32_u24_e32 v106, 0x90, v106
	v_mul_u32_u24_e32 v108, 0x90, v108
	v_mul_u32_u24_e32 v110, 0x90, v110
	v_mul_u32_u24_e32 v112, 0x90, v112
	v_mul_u32_u24_e32 v2, 0x90, v2
	v_mul_u32_u24_e32 v114, 0x90, v114
	v_mul_u32_u24_e32 v117, 0x90, v117
	v_mul_u32_u24_e32 v79, 0x90, v79
	v_add_u32_e32 v153, 0x10e00, v151
	v_cmp_lt_u32_e64 s[36:37], v0, v140
	v_cmp_gt_u32_e64 s[38:39], v0, v140
	v_cmp_eq_u32_e64 s[60:61], 0, v171
	s_movk_i32 s33, 0x180
	v_mov_b32_e32 v156, 1
	v_lshlrev_b32_e32 v132, 1, v68
	v_add_u32_e32 v157, v69, v70
	v_add_u32_e32 v158, v69, v71
	v_add_u32_e32 v159, v69, v72
	v_add_u32_e32 v160, v69, v73
	v_add_u32_e32 v161, v69, v74
	v_add_u32_e32 v171, v69, v75
	v_add_u32_e32 v172, v69, v76
	v_add_u32_e32 v173, v69, v77
	v_add_u32_e32 v174, v69, v78
	s_mov_b32 s74, 0xff800000
	v_mbcnt_hi_u32_b32 v175, -1, v139
	v_add_u32_e32 v176, v1, v80
	v_add_u32_e32 v177, v1, v81
	v_add_u32_e32 v178, v1, v82
	v_add_u32_e32 v179, v1, v83
	v_add_u32_e32 v180, v1, v100
	v_add_u32_e32 v181, v1, v101
	v_add_u32_e32 v182, v1, v102
	v_add_u32_e32 v183, v1, v103
	v_add_u32_e32 v184, v1, v104
	s_mov_b32 s75, 0x800000
	s_mov_b32 s82, 0x3f317217
	s_mov_b32 s83, 0x7f800000
	v_add_u32_e32 v185, v69, v107
	v_add_u32_e32 v186, v69, v109
	v_add_u32_e32 v187, v69, v111
	v_add_u32_e32 v188, v69, v113
	v_add_u32_e32 v189, v69, v115
	v_add_u32_e32 v190, v69, v116
	v_add_u32_e32 v191, v69, v118
	v_add_u32_e32 v192, v69, v120
	v_add_u32_e32 v193, v69, v122
	v_add_u32_e32 v194, v1, v105
	v_add_u32_e32 v195, v1, v106
	v_add_u32_e32 v196, v1, v108
	v_add_u32_e32 v197, v1, v110
	v_add_u32_e32 v198, v1, v112
	v_add_u32_e32 v199, v1, v2
	v_add_u32_e32 v200, v1, v114
	v_add_u32_e32 v201, v1, v117
	v_add_u32_e32 v202, v1, v79
	v_lshlrev_b32_e32 v134, 1, v0
	v_mov_b32_e32 v203, 0xff800000
	v_mov_b32_e32 v204, 0x41b17218
	s_waitcnt vmcnt(0)
	s_branch .LBB0_1151

.LBB0_1155:
	v_cmp_gt_i32_e32 vcc, 8, v144
	s_or_b64 s[66:67], s[66:67], exec
	s_and_saveexec_b64 s[70:71], vcc
	s_cbranch_execz .LBB0_1154
	s_cmp_lg_u32 s85, 0
	s_cbranch_scc0 .Latt_real
	s_mov_b32 s85, 0
	v_mov_b32_e32 v0, v234
	s_branch .Latt_have
.Latt_real:
	v_lshlrev_b32_e32 v2, 6, v143
	v_lshl_add_u64 v[0:1], v[2:3], 2, s[10:11]
	global_atomic_add v0, v[0:1], v156, off sc0
	s_waitcnt vmcnt(0)
.Latt_have:
	v_cmp_gt_i32_e32 vcc, s33, v0
	s_and_saveexec_b64 s[28:29], vcc
	s_xor_b64 s[72:73], exec, s[28:29]
	v_mad_u64_u32 v[130:131], s[28:29], v143, s33, v[0:1]
	s_andn2_saveexec_b64 s[72:73], s[72:73]
	s_cbranch_execz .LBB0_1153
	v_add_u32_e32 v0, 1, v143
	v_and_b32_e32 v143, 7, v0
	v_add_u32_e32 v144, 1, v144
	s_branch .LBB0_1153

.LBB0_1161:
	s_or_b64 exec, exec, s[16:17]
	v_mov_b32_e32 v0, s23
	s_waitcnt vmcnt(8)
	ds_write_b128 v151, v[64:67]
	ds_write_b128 v152, v[60:63] offset:36864
	ds_write_b128 v151, v[56:59] offset:4608
	ds_write_b128 v152, v[52:55] offset:41472
	ds_write_b128 v151, v[48:51] offset:9216
	ds_write_b128 v152, v[44:47] offset:46080
	ds_write_b128 v151, v[40:43] offset:13824
	ds_write_b128 v152, v[36:39] offset:50688
	ds_write_b128 v151, v[32:35] offset:18432
	ds_write_b128 v152, v[28:31] offset:55296
	ds_write_b128 v151, v[24:27] offset:23040
	ds_write_b128 v152, v[20:23] offset:59904
	ds_write_b128 v151, v[16:19] offset:27648
	ds_write_b128 v152, v[12:15] offset:64512
	ds_write_b128 v151, v[8:11] offset:32256
	ds_write_b128 v153, v[4:7]
	s_waitcnt lgkmcnt(0)
	s_barrier
	ds_read_b32 v0, v0
	v_mov_b32_e32 v129, v3
	v_mov_b32_e32 v133, v3
	s_waitcnt lgkmcnt(0)
	v_readfirstlane_b32 s18, v0
	s_max_i32 s16, s18, 0
	s_mul_hi_u32 s17, s16, 0xaaaaaaab
	s_lshr_b32 s17, s17, 8
	s_mul_i32 s19, s17, 0x180
	s_sub_i32 s16, s16, s19
	s_mul_i32 s19, s16, 0xaaab
	s_lshr_b32 s19, s19, 18
	s_and_b32 s19, s19, 0x3ff8
	s_lshl_b32 s16, s16, 1
	s_add_i32 s17, s17, s19
	s_and_b32 s19, s16, 0xfffe
	s_mulk_i32 s19, 0x2aab
	s_lshr_b32 s19, s19, 20
	s_mulk_i32 s19, 0x60
	s_sub_i32 s16, s16, s19
	s_mulk_i32 s17, 0x60
	s_and_b32 s16, s16, 0xfffe
	s_add_i32 s17, s17, s16
	v_add_u32_e32 v0, s17, v142
	v_mul_hi_u32 v2, v0, s25
	v_lshrrev_b32_e32 v1, 6, v2
	v_mul_lo_u32 v1, v1, s24
	v_sub_u32_e32 v0, v0, v1
	v_and_b32_e32 v1, 31, v0
	v_lshrrev_b32_e32 v0, 4, v0
	v_and_b32_e32 v76, 6, v0
	v_lshrrev_b32_e32 v4, v76, v1
	v_lshlrev_b32_e32 v69, 7, v4
	v_add_u32_e32 v6, 0xffffff80, v69
	v_lshlrev_b32_e32 v0, 3, v2
	v_or_b32_e32 v7, v6, v145
	v_cmp_eq_u32_e32 vcc, 0, v4
	v_bfe_u32 v68, v1, 0, v76
	v_and_b32_e32 v5, 0x7ffff000, v0
	v_mov_b64_e32 v[0:1], s[78:79]
	v_cndmask_b32_e64 v4, v7, 0, vcc
	v_mad_u64_u32 v[0:1], s[16:17], v5, s26, v[0:1]
	v_lshl_add_u32 v4, v4, v76, v68
	v_lshlrev_b32_e32 v2, 1, v2
	v_mad_i64_i32 v[4:5], s[16:17], v4, s26, v[0:1]
	v_and_b32_e32 v2, 0x380, v2
	v_lshl_add_u64 v[4:5], v[4:5], 0, v[2:3]
	v_lshl_add_u64 v[4:5], v[4:5], 0, v[128:129]
	v_add_co_u32_e64 v4, s[66:67], s27, v4
	v_or_b32_e32 v69, v69, v150
	s_nop 0
	v_addc_co_u32_e64 v5, s[66:67], 0, v5, s[66:67]
	global_load_dwordx4 v[64:67], v[4:5], off offset:256
	global_load_dwordx4 v[60:63], v[4:5], off offset:1280
	v_or_b32_e32 v4, 32, v7
	v_cndmask_b32_e64 v4, v4, 0, vcc
	v_lshl_add_u32 v4, v4, v76, v68
	v_mad_i64_i32 v[4:5], s[16:17], v4, s26, v[0:1]
	v_lshl_add_u64 v[4:5], v[4:5], 0, v[2:3]
	v_lshl_add_u64 v[4:5], v[4:5], 0, v[128:129]
	v_add_co_u32_e64 v4, s[66:67], s27, v4
	s_nop 1
	v_addc_co_u32_e64 v5, s[66:67], 0, v5, s[66:67]
	global_load_dwordx4 v[56:59], v[4:5], off offset:256
	global_load_dwordx4 v[52:55], v[4:5], off offset:1280
	v_or_b32_e32 v4, 64, v7
	v_cndmask_b32_e64 v4, v4, 0, vcc
	v_lshl_add_u32 v4, v4, v76, v68
	v_mad_i64_i32 v[4:5], s[16:17], v4, s26, v[0:1]
	v_lshl_add_u64 v[4:5], v[4:5], 0, v[2:3]
	v_lshl_add_u64 v[4:5], v[4:5], 0, v[128:129]
	v_add_co_u32_e64 v4, s[66:67], s27, v4
	s_nop 1
	v_addc_co_u32_e64 v5, s[66:67], 0, v5, s[66:67]
	global_load_dwordx4 v[48:51], v[4:5], off offset:256
	global_load_dwordx4 v[44:47], v[4:5], off offset:1280
	v_or_b32_e32 v4, 0x60, v7
	v_cndmask_b32_e64 v4, v4, 0, vcc
	v_lshl_add_u32 v4, v4, v76, v68
	v_mad_i64_i32 v[4:5], s[16:17], v4, s26, v[0:1]
	v_lshl_add_u64 v[4:5], v[4:5], 0, v[2:3]
	v_lshl_add_u64 v[4:5], v[4:5], 0, v[128:129]
	v_add_co_u32_e32 v4, vcc, s27, v4
	s_nop 1
	v_addc_co_u32_e32 v5, vcc, 0, v5, vcc
	global_load_dwordx4 v[40:43], v[4:5], off offset:256
	global_load_dwordx4 v[36:39], v[4:5], off offset:1280
	v_add_u32_e32 v4, v6, v146
	v_lshl_add_u32 v4, v4, v76, v68
	v_mad_u64_u32 v[4:5], s[16:17], v4, s26, v[0:1]
	v_lshl_add_u64 v[4:5], v[4:5], 0, v[2:3]
	v_lshl_add_u64 v[4:5], v[4:5], 0, v[128:129]
	v_add_co_u32_e32 v4, vcc, s27, v4
	s_nop 1
	v_addc_co_u32_e32 v5, vcc, 0, v5, vcc
	global_load_dwordx4 v[32:35], v[4:5], off offset:256
	global_load_dwordx4 v[28:31], v[4:5], off offset:1280
	v_add_u32_e32 v4, v6, v147
	v_lshl_add_u32 v4, v4, v76, v68
	v_mad_u64_u32 v[4:5], s[16:17], v4, s26, v[0:1]
	v_lshl_add_u64 v[4:5], v[4:5], 0, v[2:3]
	v_lshl_add_u64 v[4:5], v[4:5], 0, v[128:129]
	v_add_co_u32_e32 v4, vcc, s27, v4
	s_nop 1
	v_addc_co_u32_e32 v5, vcc, 0, v5, vcc
	global_load_dwordx4 v[24:27], v[4:5], off offset:256
	global_load_dwordx4 v[20:23], v[4:5], off offset:1280
	v_add_u32_e32 v4, v6, v148
	v_lshl_add_u32 v4, v4, v76, v68
	v_mad_u64_u32 v[4:5], s[16:17], v4, s26, v[0:1]
	v_lshl_add_u64 v[4:5], v[4:5], 0, v[2:3]
	v_lshl_add_u64 v[4:5], v[4:5], 0, v[128:129]
	v_add_co_u32_e32 v4, vcc, s27, v4
	s_nop 1
	v_addc_co_u32_e32 v5, vcc, 0, v5, vcc
	global_load_dwordx4 v[16:19], v[4:5], off offset:256
	global_load_dwordx4 v[12:15], v[4:5], off offset:1280
	v_add_u32_e32 v4, v6, v149
	v_lshl_add_u32 v4, v4, v76, v68
	v_mad_u64_u32 v[4:5], s[16:17], v4, s26, v[0:1]
	v_lshl_add_u64 v[4:5], v[4:5], 0, v[2:3]
	v_lshl_add_u32 v68, v69, v76, v68
	v_lshl_add_u64 v[4:5], v[4:5], 0, v[128:129]
	v_mad_u64_u32 v[0:1], s[16:17], v68, s26, v[0:1]
	v_add_co_u32_e32 v4, vcc, s27, v4
	v_lshl_add_u64 v[0:1], v[0:1], 0, v[2:3]
	v_add_u32_e32 v2, 4, v76
	v_addc_co_u32_e32 v5, vcc, 0, v5, vcc
	v_lshl_add_u64 v[0:1], v[0:1], 0, v[132:133]
	v_lshlrev_b64 v[76:77], v2, s[12:13]
	global_load_dwordx4 v[8:11], v[4:5], off offset:256
	s_nop 0
	global_load_dwordx4 v[4:7], v[4:5], off offset:1280
	s_nop 0
	global_load_dwordx4 v[68:71], v[0:1], off offset:3328
	global_load_dwordx4 v[72:75], v[0:1], off offset:3392
	v_lshl_add_u64 v[0:1], v[76:77], 1, v[0:1]
	global_load_dwordx4 v[76:79], v[0:1], off offset:3328
	global_load_dwordx4 v[80:83], v[0:1], off offset:3392
	s_and_saveexec_b64 s[68:69], s[92:93]
	s_cbranch_execz .Latt_p1done
	v_lshlrev_b32_e32 v235, 8, v143
	global_atomic_add v234, v235, v156, s[10:11] sc0
	s_mov_b32 s85, 1
.Latt_p1done:
	s_or_b64 exec, exec, s[68:69]
	ds_read_b128 v[100:103], v157
	ds_read_b128 v[104:107], v157 offset:64
	s_waitcnt lgkmcnt(1)
	v_mfma_f32_16x16x32_bf16 v[100:103], v[100:103], v[96:99], 0
	ds_read_b128 v[112:115], v171 offset:64
	s_mul_hi_u32 s16, s84, 0xaaaaaaab
	s_lshr_b32 s16, s16, 8
	s_waitcnt lgkmcnt(1)
	v_mfma_f32_16x16x32_bf16 v[208:211], v[104:107], v[92:95], v[100:103]
	ds_read_b128 v[104:107], v158 offset:64
	ds_read_b128 v[120:123], v172 offset:64
	s_mul_i32 s17, s16, 0x180
	ds_read_b128 v[100:103], v158
	s_waitcnt lgkmcnt(0)
	v_mfma_f32_16x16x32_bf16 v[100:103], v[100:103], v[96:99], 0
	ds_read_b128 v[212:215], v173 offset:64
	s_sub_i32 s17, s84, s17
	s_mul_i32 s19, s17, 0xaaab
	v_mfma_f32_16x16x32_bf16 v[124:127], v[104:107], v[92:95], v[100:103]
	ds_read_b128 v[104:107], v159 offset:64
	s_lshr_b32 s19, s19, 18
	s_and_b32 s19, s19, 0x3ff8
	s_nop 0
	ds_read_b128 v[100:103], v159
	s_waitcnt lgkmcnt(0)
	v_mfma_f32_16x16x32_bf16 v[100:103], v[100:103], v[96:99], 0
	s_lshl_b32 s17, s17, 1
	s_add_i32 s16, s16, s19
	s_and_b32 s19, s17, 0xfffe
	v_mfma_f32_16x16x32_bf16 v[116:119], v[104:107], v[92:95], v[100:103]
	ds_read_b128 v[104:107], v160 offset:64
	s_mulk_i32 s19, 0x2aab
	s_lshr_b32 s19, s19, 20
	s_nop 0
	ds_read_b128 v[100:103], v160
	s_waitcnt lgkmcnt(0)
	v_mfma_f32_16x16x32_bf16 v[100:103], v[100:103], v[96:99], 0
	s_mulk_i32 s19, 0x60
	s_sub_i32 s17, s17, s19
	s_mulk_i32 s16, 0x60
	v_mfma_f32_16x16x32_bf16 v[108:111], v[104:107], v[92:95], v[100:103]
	ds_read_b128 v[104:107], v161 offset:64
	s_and_b32 s17, s17, 0xfffe
	s_add_i32 s16, s16, s17
	s_nop 0
	ds_read_b128 v[100:103], v161
	s_waitcnt lgkmcnt(0)
	v_mfma_f32_16x16x32_bf16 v[100:103], v[100:103], v[96:99], 0
	v_add_u32_e32 v0, s16, v142
	v_mul_hi_u32 v1, v0, s25
	v_lshrrev_b32_e32 v135, 6, v1
	v_mfma_f32_16x16x32_bf16 v[104:107], v[104:107], v[92:95], v[100:103]
	v_mul_lo_u32 v1, v135, s24
	v_sub_u32_e32 v0, v0, v1
	v_lshrrev_b32_e32 v131, 5, v0
	s_nop 0
	ds_read_b128 v[100:103], v171
	s_waitcnt lgkmcnt(0)
	v_mfma_f32_16x16x32_bf16 v[100:103], v[100:103], v[96:99], 0
	v_and_b32_e32 v206, 31, v0
	v_lshlrev_b32_e32 v129, 1, v131
	v_lshrrev_b32_e32 v0, v129, v206
	v_mfma_f32_16x16x32_bf16 v[100:103], v[112:115], v[92:95], v[100:103]
	ds_read_b128 v[112:115], v172
	v_mov_b32_e32 v2, s74
	v_cndmask_b32_e64 v1, v211, v203, s[46:47]
	s_waitcnt lgkmcnt(0)
	v_mfma_f32_16x16x32_bf16 v[112:115], v[112:115], v[96:99], 0
	v_cmp_eq_u32_e64 s[66:67], 0, v0
	v_mfma_f32_16x16x32_bf16 v[112:115], v[120:123], v[92:95], v[112:115]
	ds_read_b128 v[120:123], v173
	s_waitcnt lgkmcnt(0)
	v_mfma_f32_16x16x32_bf16 v[120:123], v[120:123], v[96:99], 0
	v_mfma_f32_16x16x32_bf16 v[120:123], v[212:215], v[92:95], v[120:123]
	ds_read_b128 v[212:215], v174
	s_waitcnt lgkmcnt(0)
	v_mfma_f32_16x16x32_bf16 v[96:99], v[212:215], v[96:99], 0
	ds_read_b128 v[212:215], v174 offset:64
	s_waitcnt lgkmcnt(0)
	v_mfma_f32_16x16x32_bf16 v[92:95], v[212:215], v[92:95], v[96:99]
	s_nop 4
	v_cndmask_b32_e64 v99, v208, v2, s[36:37]
	v_cndmask_b32_e64 v98, v209, v203, s[40:41]
	v_cndmask_b32_e64 v2, v210, v203, s[42:43]
	s_and_saveexec_b64 s[16:17], s[66:67]
	s_cbranch_execz .LBB0_1163
	v_mov_b32_e32 v124, 0xff800000
	v_cndmask_b32_e64 v119, v203, v119, s[50:51]
	v_cndmask_b32_e64 v118, v203, v118, s[50:51]
	v_cndmask_b32_e64 v117, v203, v117, s[50:51]
	v_cndmask_b32_e64 v116, v203, v116, s[50:51]
	v_cndmask_b32_e64 v111, v111, v203, s[52:53]
	v_cndmask_b32_e64 v110, v110, v203, s[52:53]
	v_cndmask_b32_e64 v109, v109, v203, s[52:53]
	v_cndmask_b32_e64 v108, v108, v203, s[52:53]
	v_cndmask_b32_e64 v107, v107, v203, s[54:55]
	v_cndmask_b32_e64 v106, v106, v203, s[54:55]
	v_cndmask_b32_e64 v105, v105, v203, s[54:55]
	v_cndmask_b32_e64 v104, v104, v203, s[54:55]
	v_cndmask_b32_e64 v103, v103, v203, s[56:57]
	v_cndmask_b32_e64 v102, v102, v203, s[56:57]
	v_cndmask_b32_e64 v101, v101, v203, s[56:57]
	v_cndmask_b32_e64 v100, v100, v203, s[56:57]
	v_cndmask_b32_e64 v115, v115, v203, s[58:59]
	v_cndmask_b32_e64 v114, v114, v203, s[58:59]
	v_cndmask_b32_e64 v113, v113, v203, s[58:59]
	v_cndmask_b32_e64 v112, v112, v203, s[58:59]
	v_cndmask_b32_e64 v123, v123, v203, s[58:59]
	v_cndmask_b32_e64 v122, v122, v203, s[58:59]
	v_cndmask_b32_e64 v121, v121, v203, s[58:59]
	v_cndmask_b32_e64 v120, v120, v203, s[58:59]
	v_mov_b32_e32 v125, v124
	v_mov_b32_e32 v126, v124
	v_mov_b32_e32 v127, v124
	v_mov_b32_e32 v99, v124
	v_mov_b32_e32 v98, v124
	v_mov_b32_e32 v2, v124
	v_mov_b32_e32 v1, v124

.LBB0_1221:
	s_or_b64 exec, exec, s[10:11]
	s_cmpk_lt_i32 s2, 0x800
	s_cselect_b64 s[10:11], -1, 0
	s_and_b64 vcc, exec, s[10:11]
	s_waitcnt lgkmcnt(0)
	s_barrier
	s_cbranch_vccz .LBB0_1224
	v_readlane_b32 s46, v246, 38
	v_readlane_b32 s47, v246, 39
	v_readlane_b32 s48, v246, 40
	v_readlane_b32 s49, v246, 41
	v_lshrrev_b32_e32 v0, 6, v141
	v_and_b32_e32 v1, 63, v141
	s_mov_b32 s44, 0xbfb8aa3b
	v_readfirstlane_b32 s13, v0
	s_mov_b32 s45, 0xbfb8aa3b
	v_lshlrev_b32_e32 v4, 4, v1
	v_lshrrev_b32_e32 v2, 3, v1
	v_lshlrev_b32_e32 v0, 5, v1
	v_lshlrev_b32_e32 v5, 2, v2
	v_mul_u32_u24_e32 v6, 0x318000, v2
	global_load_dwordx4 v[8:11], v0, s[46:47]
	global_load_dwordx4 v[12:15], v0, s[46:47] offset:16
	global_load_dwordx4 v[16:19], v0, s[48:49]
	global_load_dwordx4 v[20:23], v0, s[48:49] offset:16
	v_and_b32_e32 v7, 7, v1
	v_lshrrev_b32_e32 v2, 1, v7
	v_and_b32_e32 v7, 1, v7
	v_lshlrev_b32_e32 v2, 9, v2
	v_lshlrev_b32_e32 v7, 6, v7
	v_add3_u32 v7, v6, v2, v7
	v_mov_b32_e32 v100, 0x3a27c5ac
	v_and_b32_e32 v101, 15, v1
	v_lshlrev_b32_e32 v101, 2, v101
	s_add_i32 s16, s2, 0
	s_and_b32 s17, s16, 7
	s_lshr_b32 s12, s16, 3
	s_add_i32 s22, s90, 0
	s_lshr_b32 s22, s22, 3
	s_lshl_b32 s91, s17, 12
	s_add_i32 s91, s91, s13
	s_lshl_b32 s17, s17, 6
	s_add_i32 s17, s17, 0x4000
	s_add_u32 s74, s88, s17
	s_addc_u32 s75, s89, 0
	s_movk_i32 s56, 0x8000
	s_lshl_b32 s16, s12, 4
	s_add_i32 s16, s16, s91
	s_mul_i32 s17, s16, 0x2100
	s_add_u32 s24, s78, s17
	s_addc_u32 s25, s79, 0
	s_add_u32 s26, s24, 0x1900
	s_addc_u32 s27, s25, 0
	s_lshl_b32 s17, s16, 10
	s_add_u32 s28, s80, s17
	s_addc_u32 s29, s81, 0
	s_lshr_b32 s17, s16, 12
	s_lshl_b32 s17, s17, 11
	s_bfe_u32 s19, s16, 0x80004
	s_add_i32 s17, s17, s19
	s_mul_i32 s17, s17, 0x3180
	s_add_u32 s68, s86, s17
	s_addc_u32 s69, s87, 0
	s_and_b32 s19, s16, 15
	s_lshl_b32 s17, s19, 2
	s_addk_i32 s17, 0x3100
	s_add_u32 s30, s68, s17
	s_addc_u32 s31, s69, 0
	s_lshr_b32 s17, s19, 2
	s_lshl_b32 s17, s17, 7
	s_and_b32 s19, s19, 3
	s_lshl_b32 s19, s19, 1
	s_add_i32 s17, s17, s19
	s_addk_i32 s17, 0x2800
	s_add_u32 s70, s68, s17
	s_addc_u32 s71, s69, 0
	global_load_dword v24, v5, s[24:25] offset:3072
	global_load_dword v25, v5, s[24:25] offset:3104
	global_load_dword v26, v5, s[24:25] offset:3136
	global_load_dwordx4 v[28:31], v4, s[24:25] nt
	global_load_dwordx4 v[32:35], v4, s[24:25] offset:1024 nt
	global_load_dwordx4 v[36:39], v4, s[24:25] offset:2048 nt
	global_load_dwordx4 v[44:47], v4, s[26:27] offset:1024 nt
	global_load_dwordx4 v[48:51], v4, s[28:29] nt
	global_load_dwordx4 v[52:55], v4, s[26:27] nt
	global_load_dword v27, v6, s[30:31]
	global_load_ushort v56, v7, s[70:71] offset:0
	global_load_ushort v57, v7, s[70:71] offset:8
	global_load_ushort v58, v7, s[70:71] offset:16
	global_load_ushort v59, v7, s[70:71] offset:24
	global_load_ushort v60, v7, s[70:71] offset:32
	global_load_ushort v61, v7, s[70:71] offset:40
	global_load_ushort v62, v7, s[70:71] offset:48
	global_load_ushort v63, v7, s[70:71] offset:56
	s_mov_b32 s50, 1
.Lfm_loop:
	s_lshl_b32 s16, s12, 4
	s_add_i32 s16, s16, s91
	s_add_i32 s16, s16, 8
	s_mul_i32 s17, s16, 0x2100
	s_add_u32 s58, s78, s17
	s_addc_u32 s59, s79, 0
	s_add_u32 s60, s58, 0x1900
	s_addc_u32 s61, s59, 0
	s_lshl_b32 s17, s16, 10
	s_add_u32 s62, s80, s17
	s_addc_u32 s63, s81, 0
	s_lshr_b32 s17, s16, 12
	s_lshl_b32 s17, s17, 11
	s_bfe_u32 s19, s16, 0x80004
	s_add_i32 s17, s17, s19
	s_mul_i32 s17, s17, 0x3180
	s_add_u32 s68, s86, s17
	s_addc_u32 s69, s87, 0
	s_and_b32 s19, s16, 15
	s_lshl_b32 s17, s19, 2
	s_addk_i32 s17, 0x3100
	s_add_u32 s64, s68, s17
	s_addc_u32 s65, s69, 0
	s_lshr_b32 s17, s19, 2
	s_lshl_b32 s17, s17, 7
	s_and_b32 s19, s19, 3
	s_lshl_b32 s19, s19, 1
	s_add_i32 s17, s17, s19
	s_addk_i32 s17, 0x2800
	s_add_u32 s66, s68, s17
	s_addc_u32 s67, s69, 0
	global_load_dword v64, v5, s[58:59] offset:3072
	global_load_dword v65, v5, s[58:59] offset:3104
	global_load_dword v66, v5, s[58:59] offset:3136
	global_load_dwordx4 v[68:71], v4, s[58:59] nt
	global_load_dwordx4 v[72:75], v4, s[58:59] offset:1024 nt
	global_load_dwordx4 v[76:79], v4, s[58:59] offset:2048 nt
	global_load_dwordx4 v[80:83], v4, s[60:61] offset:1024 nt
	global_load_dwordx4 v[84:87], v4, s[62:63] nt
	global_load_dwordx4 v[88:91], v4, s[60:61] nt
	global_load_dword v67, v6, s[64:65]
	global_load_ushort v92, v7, s[66:67] offset:0
	global_load_ushort v93, v7, s[66:67] offset:8
	global_load_ushort v94, v7, s[66:67] offset:16
	global_load_ushort v95, v7, s[66:67] offset:24
	global_load_ushort v96, v7, s[66:67] offset:32
	global_load_ushort v97, v7, s[66:67] offset:40
	global_load_ushort v98, v7, s[66:67] offset:48
	global_load_ushort v99, v7, s[66:67] offset:56
	s_cmp_eq_u32 s50, 0
	s_cbranch_scc1 .Lfm_w20
	s_waitcnt vmcnt(18)
	s_branch .Lfm_wdone

.Lfm_wdone:
	v_max3_f32 v127, v24, v25, v26
	v_sub_f32_e32 v102, v24, v127
	v_sub_f32_e32 v104, v25, v127
	v_sub_f32_e32 v106, v26, v127
	v_mul_f32_e32 v102, 0x3fb8aa3b, v102
	v_mul_f32_e32 v104, 0x3fb8aa3b, v104
	v_mul_f32_e32 v106, 0x3fb8aa3b, v106
	v_exp_f32_e32 v102, v102
	v_exp_f32_e32 v104, v104
	v_exp_f32_e32 v106, v106
	s_nop 0
	v_add_f32_e32 v127, v102, v104
	v_add_f32_e32 v127, v106, v127
	v_div_scale_f32 v122, s[72:73], v127, v127, 1.0
	v_rcp_f32_e32 v123, v122
	v_div_scale_f32 v124, vcc, 1.0, v127, 1.0
	v_fma_f32 v126, -v122, v123, 1.0
	v_fmac_f32_e32 v123, v126, v123
	v_mul_f32_e32 v125, v124, v123
	v_fma_f32 v126, -v122, v125, v124
	v_fmac_f32_e32 v125, v126, v123
	v_fma_f32 v122, -v122, v125, v124
	v_div_fmas_f32 v122, v122, v123, v125
	v_div_fixup_f32 v103, v122, v127, 1.0
	v_mul_f32_e32 v102, v102, v103
	v_mul_f32_e32 v104, v104, v103
	v_mul_f32_e32 v106, v106, v103
	v_lshlrev_b32_e32 v108, 16, v28
	v_and_b32_e32 v109, 0xffff0000, v28
	v_lshlrev_b32_e32 v110, 16, v32
	v_and_b32_e32 v111, 0xffff0000, v32
	v_lshlrev_b32_e32 v112, 16, v36
	v_and_b32_e32 v113, 0xffff0000, v36
	v_lshlrev_b32_e32 v114, 16, v44
	v_and_b32_e32 v115, 0xffff0000, v44
	v_pk_mul_f32 v[116:117], v[108:109], v[102:103] op_sel_hi:[1,0]
	v_pk_fma_f32 v[116:117], v[110:111], v[104:105], v[116:117] op_sel_hi:[1,0,1]
	v_pk_fma_f32 v[116:117], v[112:113], v[106:107], v[116:117] op_sel_hi:[1,0,1]
	v_pk_mul_f32 v[118:119], v[114:115], s[44:45]
	v_exp_f32_e32 v118, v118
	v_exp_f32_e32 v119, v119
	s_nop 0
	v_pk_add_f32 v[118:119], v[118:119], 1.0 op_sel_hi:[1,0]
	v_div_scale_f32 v122, s[72:73], v118, v118, v114
	v_rcp_f32_e32 v123, v122
	v_div_scale_f32 v124, vcc, v114, v118, v114
	v_fma_f32 v126, -v122, v123, 1.0
	v_fmac_f32_e32 v123, v126, v123
	v_mul_f32_e32 v125, v124, v123
	v_fma_f32 v126, -v122, v125, v124
	v_fmac_f32_e32 v125, v126, v123
	v_fma_f32 v122, -v122, v125, v124
	v_div_fmas_f32 v122, v122, v123, v125
	v_div_fixup_f32 v120, v122, v118, v114
	v_div_scale_f32 v122, s[72:73], v119, v119, v115
	v_rcp_f32_e32 v123, v122
	v_div_scale_f32 v124, vcc, v115, v119, v115
	v_fma_f32 v126, -v122, v123, 1.0
	v_fmac_f32_e32 v123, v126, v123
	v_mul_f32_e32 v125, v124, v123
	v_fma_f32 v126, -v122, v125, v124
	v_fmac_f32_e32 v125, v126, v123
	v_fma_f32 v122, -v122, v125, v124
	v_div_fmas_f32 v122, v122, v123, v125
	v_div_fixup_f32 v121, v122, v119, v115
	v_pk_mul_f32 v[116:117], v[120:121], v[116:117]
	v_cvt_pk_bf16_f32 v128, v116, v117
	v_lshlrev_b32_e32 v108, 16, v29
	v_and_b32_e32 v109, 0xffff0000, v29
	v_lshlrev_b32_e32 v110, 16, v33
	v_and_b32_e32 v111, 0xffff0000, v33
	v_lshlrev_b32_e32 v112, 16, v37
	v_and_b32_e32 v113, 0xffff0000, v37
	v_lshlrev_b32_e32 v114, 16, v45
	v_and_b32_e32 v115, 0xffff0000, v45
	v_pk_mul_f32 v[116:117], v[108:109], v[102:103] op_sel_hi:[1,0]
	v_pk_fma_f32 v[116:117], v[110:111], v[104:105], v[116:117] op_sel_hi:[1,0,1]
	v_pk_fma_f32 v[116:117], v[112:113], v[106:107], v[116:117] op_sel_hi:[1,0,1]
	v_pk_mul_f32 v[118:119], v[114:115], s[44:45]
	v_exp_f32_e32 v118, v118
	v_exp_f32_e32 v119, v119
	s_nop 0
	v_pk_add_f32 v[118:119], v[118:119], 1.0 op_sel_hi:[1,0]
	v_div_scale_f32 v122, s[72:73], v118, v118, v114
	v_rcp_f32_e32 v123, v122
	v_div_scale_f32 v124, vcc, v114, v118, v114
	v_fma_f32 v126, -v122, v123, 1.0
	v_fmac_f32_e32 v123, v126, v123
	v_mul_f32_e32 v125, v124, v123
	v_fma_f32 v126, -v122, v125, v124
	v_fmac_f32_e32 v125, v126, v123
	v_fma_f32 v122, -v122, v125, v124
	v_div_fmas_f32 v122, v122, v123, v125
	v_div_fixup_f32 v120, v122, v118, v114
	v_div_scale_f32 v122, s[72:73], v119, v119, v115
	v_rcp_f32_e32 v123, v122
	v_div_scale_f32 v124, vcc, v115, v119, v115
	v_fma_f32 v126, -v122, v123, 1.0
	v_fmac_f32_e32 v123, v126, v123
	v_mul_f32_e32 v125, v124, v123
	v_fma_f32 v126, -v122, v125, v124
	v_fmac_f32_e32 v125, v126, v123
	v_fma_f32 v122, -v122, v125, v124
	v_div_fmas_f32 v122, v122, v123, v125
	v_div_fixup_f32 v121, v122, v119, v115
	v_pk_mul_f32 v[116:117], v[120:121], v[116:117]
	v_cvt_pk_bf16_f32 v129, v116, v117
	v_lshlrev_b32_e32 v108, 16, v30
	v_and_b32_e32 v109, 0xffff0000, v30
	v_lshlrev_b32_e32 v110, 16, v34
	v_and_b32_e32 v111, 0xffff0000, v34
	v_lshlrev_b32_e32 v112, 16, v38
	v_and_b32_e32 v113, 0xffff0000, v38
	v_lshlrev_b32_e32 v114, 16, v46
	v_and_b32_e32 v115, 0xffff0000, v46
	v_pk_mul_f32 v[116:117], v[108:109], v[102:103] op_sel_hi:[1,0]
	v_pk_fma_f32 v[116:117], v[110:111], v[104:105], v[116:117] op_sel_hi:[1,0,1]
	v_pk_fma_f32 v[116:117], v[112:113], v[106:107], v[116:117] op_sel_hi:[1,0,1]
	v_pk_mul_f32 v[118:119], v[114:115], s[44:45]
	v_exp_f32_e32 v118, v118
	v_exp_f32_e32 v119, v119
	s_nop 0
	v_pk_add_f32 v[118:119], v[118:119], 1.0 op_sel_hi:[1,0]
	v_div_scale_f32 v122, s[72:73], v118, v118, v114
	v_rcp_f32_e32 v123, v122
	v_div_scale_f32 v124, vcc, v114, v118, v114
	v_fma_f32 v126, -v122, v123, 1.0
	v_fmac_f32_e32 v123, v126, v123
	v_mul_f32_e32 v125, v124, v123
	v_fma_f32 v126, -v122, v125, v124
	v_fmac_f32_e32 v125, v126, v123
	v_fma_f32 v122, -v122, v125, v124
	v_div_fmas_f32 v122, v122, v123, v125
	v_div_fixup_f32 v120, v122, v118, v114
	v_div_scale_f32 v122, s[72:73], v119, v119, v115
	v_rcp_f32_e32 v123, v122
	v_div_scale_f32 v124, vcc, v115, v119, v115
	v_fma_f32 v126, -v122, v123, 1.0
	v_fmac_f32_e32 v123, v126, v123
	v_mul_f32_e32 v125, v124, v123
	v_fma_f32 v126, -v122, v125, v124
	v_fmac_f32_e32 v125, v126, v123
	v_fma_f32 v122, -v122, v125, v124
	v_div_fmas_f32 v122, v122, v123, v125
	v_div_fixup_f32 v121, v122, v119, v115
	v_pk_mul_f32 v[116:117], v[120:121], v[116:117]
	v_cvt_pk_bf16_f32 v130, v116, v117
	v_lshlrev_b32_e32 v108, 16, v31
	v_and_b32_e32 v109, 0xffff0000, v31
	v_lshlrev_b32_e32 v110, 16, v35
	v_and_b32_e32 v111, 0xffff0000, v35
	v_lshlrev_b32_e32 v112, 16, v39
	v_and_b32_e32 v113, 0xffff0000, v39
	v_lshlrev_b32_e32 v114, 16, v47
	v_and_b32_e32 v115, 0xffff0000, v47
	v_pk_mul_f32 v[116:117], v[108:109], v[102:103] op_sel_hi:[1,0]
	v_pk_fma_f32 v[116:117], v[110:111], v[104:105], v[116:117] op_sel_hi:[1,0,1]
	v_pk_fma_f32 v[116:117], v[112:113], v[106:107], v[116:117] op_sel_hi:[1,0,1]
	v_pk_mul_f32 v[118:119], v[114:115], s[44:45]
	v_exp_f32_e32 v118, v118
	v_exp_f32_e32 v119, v119
	s_nop 0
	v_pk_add_f32 v[118:119], v[118:119], 1.0 op_sel_hi:[1,0]
	v_div_scale_f32 v122, s[72:73], v118, v118, v114
	v_rcp_f32_e32 v123, v122
	v_div_scale_f32 v124, vcc, v114, v118, v114
	v_fma_f32 v126, -v122, v123, 1.0
	v_fmac_f32_e32 v123, v126, v123
	v_mul_f32_e32 v125, v124, v123
	v_fma_f32 v126, -v122, v125, v124
	v_fmac_f32_e32 v125, v126, v123
	v_fma_f32 v122, -v122, v125, v124
	v_div_fmas_f32 v122, v122, v123, v125
	v_div_fixup_f32 v120, v122, v118, v114
	v_div_scale_f32 v122, s[72:73], v119, v119, v115
	v_rcp_f32_e32 v123, v122
	v_div_scale_f32 v124, vcc, v115, v119, v115
	v_fma_f32 v126, -v122, v123, 1.0
	v_fmac_f32_e32 v123, v126, v123
	v_mul_f32_e32 v125, v124, v123
	v_fma_f32 v126, -v122, v125, v124
	v_fmac_f32_e32 v125, v126, v123
	v_fma_f32 v122, -v122, v125, v124
	v_div_fmas_f32 v122, v122, v123, v125
	v_div_fixup_f32 v121, v122, v119, v115
	v_pk_mul_f32 v[116:117], v[120:121], v[116:117]
	v_cvt_pk_bf16_f32 v131, v116, v117
	global_store_dwordx4 v4, v[128:131], s[26:27] offset:1024
	v_lshlrev_b32_e32 v28, 16, v48
	v_and_b32_e32 v29, 0xffff0000, v48
	v_lshlrev_b32_e32 v30, 16, v49
	v_and_b32_e32 v31, 0xffff0000, v49
	v_lshlrev_b32_e32 v32, 16, v50
	v_and_b32_e32 v33, 0xffff0000, v50
	v_lshlrev_b32_e32 v34, 16, v51
	v_and_b32_e32 v35, 0xffff0000, v51
	v_lshlrev_b32_e32 v36, 16, v52
	v_and_b32_e32 v37, 0xffff0000, v52
	v_lshlrev_b32_e32 v38, 16, v53
	v_and_b32_e32 v39, 0xffff0000, v53
	v_lshlrev_b32_e32 v44, 16, v54
	v_and_b32_e32 v45, 0xffff0000, v54
	v_lshlrev_b32_e32 v46, 16, v55
	v_and_b32_e32 v47, 0xffff0000, v55
	v_lshlrev_b32_e32 v56, 16, v56
	v_lshlrev_b32_e32 v57, 16, v57
	v_lshlrev_b32_e32 v58, 16, v58
	v_lshlrev_b32_e32 v59, 16, v59
	v_lshlrev_b32_e32 v60, 16, v60
	v_lshlrev_b32_e32 v61, 16, v61
	v_lshlrev_b32_e32 v62, 16, v62
	v_lshlrev_b32_e32 v63, 16, v63
	v_add_f32_e32 v108, v28, v29
	v_add_f32_e32 v108, v108, v30
	v_add_f32_e32 v108, v108, v31
	v_add_f32_e32 v108, v108, v32
	v_add_f32_e32 v108, v108, v33
	v_add_f32_e32 v108, v108, v34
	v_add_f32_e32 v108, v108, v35
	s_nop 1
	v_add_f32_dpp v109, v108, v108 quad_perm:[1,0,3,2] row_mask:0xf bank_mask:0xf
	s_nop 1
	v_add_f32_dpp v108, v109, v109 quad_perm:[2,3,0,1] row_mask:0xf bank_mask:0xf
	s_nop 1
	v_add_f32_dpp v109, v108, v108 row_half_mirror row_mask:0xf bank_mask:0xf
	v_mov_b32_e32 v108, v109
	v_mul_f32_e32 v108, 0x3c800000, v108
	v_pk_add_f32 v[28:29], v[28:29], v[108:109] op_sel_hi:[1,0] neg_lo:[0,1] neg_hi:[0,1]
	v_pk_add_f32 v[30:31], v[30:31], v[108:109] op_sel_hi:[1,0] neg_lo:[0,1] neg_hi:[0,1]
	v_pk_add_f32 v[32:33], v[32:33], v[108:109] op_sel_hi:[1,0] neg_lo:[0,1] neg_hi:[0,1]
	v_pk_add_f32 v[34:35], v[34:35], v[108:109] op_sel_hi:[1,0] neg_lo:[0,1] neg_hi:[0,1]
	v_pk_mul_f32 v[110:111], v[28:29], v[28:29]
	v_pk_mul_f32 v[112:113], v[30:31], v[30:31]
	v_pk_mul_f32 v[114:115], v[32:33], v[32:33]
	v_pk_mul_f32 v[116:117], v[34:35], v[34:35]
	v_add_f32_e32 v118, v110, v111
	v_add_f32_e32 v118, v112, v118
	v_add_f32_e32 v118, v113, v118
	v_add_f32_e32 v118, v114, v118
	v_add_f32_e32 v118, v115, v118
	v_add_f32_e32 v118, v116, v118
	v_add_f32_e32 v118, v117, v118
	s_nop 1
	v_add_f32_dpp v119, v118, v118 quad_perm:[1,0,3,2] row_mask:0xf bank_mask:0xf
	s_nop 1
	v_add_f32_dpp v118, v119, v119 quad_perm:[2,3,0,1] row_mask:0xf bank_mask:0xf
	s_nop 1
	v_add_f32_dpp v119, v118, v118 row_half_mirror row_mask:0xf bank_mask:0xf
	v_mov_b32_e32 v118, v119
	v_fmamk_f32 v118, v118, 0x3c800000, v100
	v_rsq_f32_e32 v118, v118
	v_mov_b32_e32 v120, v27
	v_pk_mul_f32 v[28:29], v[28:29], v[118:119] op_sel_hi:[1,0]
	v_pk_mul_f32 v[30:31], v[30:31], v[118:119] op_sel_hi:[1,0]
	v_pk_mul_f32 v[32:33], v[32:33], v[118:119] op_sel_hi:[1,0]
	v_pk_mul_f32 v[34:35], v[34:35], v[118:119] op_sel_hi:[1,0]
	v_pk_fma_f32 v[28:29], v[8:9], v[28:29], v[16:17]
	v_pk_fma_f32 v[30:31], v[10:11], v[30:31], v[18:19]
	v_pk_fma_f32 v[32:33], v[12:13], v[32:33], v[20:21]
	v_pk_fma_f32 v[34:35], v[14:15], v[34:35], v[22:23]
	v_pk_fma_f32 v[28:29], v[120:121], v[56:57], v[28:29] op_sel_hi:[0,1,1]
	v_pk_fma_f32 v[30:31], v[120:121], v[58:59], v[30:31] op_sel_hi:[0,1,1]
	v_pk_fma_f32 v[32:33], v[120:121], v[60:61], v[32:33] op_sel_hi:[0,1,1]
	v_pk_fma_f32 v[34:35], v[120:121], v[62:63], v[34:35] op_sel_hi:[0,1,1]
	v_pk_mul_f32 v[118:119], v[36:37], s[44:45]
	v_exp_f32_e32 v118, v118
	v_exp_f32_e32 v119, v119
	s_nop 0
	v_pk_add_f32 v[118:119], v[118:119], 1.0 op_sel_hi:[1,0]
	v_div_scale_f32 v122, s[72:73], v118, v118, v36
	v_rcp_f32_e32 v123, v122
	v_div_scale_f32 v124, vcc, v36, v118, v36
	v_fma_f32 v126, -v122, v123, 1.0
	v_fmac_f32_e32 v123, v126, v123
	v_mul_f32_e32 v125, v124, v123
	v_fma_f32 v126, -v122, v125, v124
	v_fmac_f32_e32 v125, v126, v123
	v_fma_f32 v122, -v122, v125, v124
	v_div_fmas_f32 v122, v122, v123, v125
	v_div_fixup_f32 v108, v122, v118, v36
	v_div_scale_f32 v122, s[72:73], v119, v119, v37
	v_rcp_f32_e32 v123, v122
	v_div_scale_f32 v124, vcc, v37, v119, v37
	v_fma_f32 v126, -v122, v123, 1.0
	v_fmac_f32_e32 v123, v126, v123
	v_mul_f32_e32 v125, v124, v123
	v_fma_f32 v126, -v122, v125, v124
	v_fmac_f32_e32 v125, v126, v123
	v_fma_f32 v122, -v122, v125, v124
	v_div_fmas_f32 v122, v122, v123, v125
	v_div_fixup_f32 v109, v122, v119, v37
	v_pk_mul_f32 v[28:29], v[108:109], v[28:29]
	v_cvt_pk_bf16_f32 v132, v28, v29
	v_pk_mul_f32 v[118:119], v[38:39], s[44:45]
	v_exp_f32_e32 v118, v118
	v_exp_f32_e32 v119, v119
	s_nop 0
	v_pk_add_f32 v[118:119], v[118:119], 1.0 op_sel_hi:[1,0]
	v_div_scale_f32 v122, s[72:73], v118, v118, v38
	v_rcp_f32_e32 v123, v122
	v_div_scale_f32 v124, vcc, v38, v118, v38
	v_fma_f32 v126, -v122, v123, 1.0
	v_fmac_f32_e32 v123, v126, v123
	v_mul_f32_e32 v125, v124, v123
	v_fma_f32 v126, -v122, v125, v124
	v_fmac_f32_e32 v125, v126, v123
	v_fma_f32 v122, -v122, v125, v124
	v_div_fmas_f32 v122, v122, v123, v125
	v_div_fixup_f32 v108, v122, v118, v38
	v_div_scale_f32 v122, s[72:73], v119, v119, v39
	v_rcp_f32_e32 v123, v122
	v_div_scale_f32 v124, vcc, v39, v119, v39
	v_fma_f32 v126, -v122, v123, 1.0
	v_fmac_f32_e32 v123, v126, v123
	v_mul_f32_e32 v125, v124, v123
	v_fma_f32 v126, -v122, v125, v124
	v_fmac_f32_e32 v125, v126, v123
	v_fma_f32 v122, -v122, v125, v124
	v_div_fmas_f32 v122, v122, v123, v125
	v_div_fixup_f32 v109, v122, v119, v39
	v_pk_mul_f32 v[30:31], v[108:109], v[30:31]
	v_cvt_pk_bf16_f32 v133, v30, v31
	v_pk_mul_f32 v[118:119], v[44:45], s[44:45]
	v_exp_f32_e32 v118, v118
	v_exp_f32_e32 v119, v119
	s_nop 0
	v_pk_add_f32 v[118:119], v[118:119], 1.0 op_sel_hi:[1,0]
	v_div_scale_f32 v122, s[72:73], v118, v118, v44
	v_rcp_f32_e32 v123, v122
	v_div_scale_f32 v124, vcc, v44, v118, v44
	v_fma_f32 v126, -v122, v123, 1.0
	v_fmac_f32_e32 v123, v126, v123
	v_mul_f32_e32 v125, v124, v123
	v_fma_f32 v126, -v122, v125, v124
	v_fmac_f32_e32 v125, v126, v123
	v_fma_f32 v122, -v122, v125, v124
	v_div_fmas_f32 v122, v122, v123, v125
	v_div_fixup_f32 v108, v122, v118, v44
	v_div_scale_f32 v122, s[72:73], v119, v119, v45
	v_rcp_f32_e32 v123, v122
	v_div_scale_f32 v124, vcc, v45, v119, v45
	v_fma_f32 v126, -v122, v123, 1.0
	v_fmac_f32_e32 v123, v126, v123
	v_mul_f32_e32 v125, v124, v123
	v_fma_f32 v126, -v122, v125, v124
	v_fmac_f32_e32 v125, v126, v123
	v_fma_f32 v122, -v122, v125, v124
	v_div_fmas_f32 v122, v122, v123, v125
	v_div_fixup_f32 v109, v122, v119, v45
	v_pk_mul_f32 v[32:33], v[108:109], v[32:33]
	v_cvt_pk_bf16_f32 v134, v32, v33
	v_pk_mul_f32 v[118:119], v[46:47], s[44:45]
	v_exp_f32_e32 v118, v118
	v_exp_f32_e32 v119, v119
	s_nop 0
	v_pk_add_f32 v[118:119], v[118:119], 1.0 op_sel_hi:[1,0]
	v_div_scale_f32 v122, s[72:73], v118, v118, v46
	v_rcp_f32_e32 v123, v122
	v_div_scale_f32 v124, vcc, v46, v118, v46
	v_fma_f32 v126, -v122, v123, 1.0
	v_fmac_f32_e32 v123, v126, v123
	v_mul_f32_e32 v125, v124, v123
	v_fma_f32 v126, -v122, v125, v124
	v_fmac_f32_e32 v125, v126, v123
	v_fma_f32 v122, -v122, v125, v124
	v_div_fmas_f32 v122, v122, v123, v125
	v_div_fixup_f32 v108, v122, v118, v46
	v_div_scale_f32 v122, s[72:73], v119, v119, v47
	v_rcp_f32_e32 v123, v122
	v_div_scale_f32 v124, vcc, v47, v119, v47
	v_fma_f32 v126, -v122, v123, 1.0
	v_fmac_f32_e32 v123, v126, v123
	v_mul_f32_e32 v125, v124, v123
	v_fma_f32 v126, -v122, v125, v124
	v_fmac_f32_e32 v125, v126, v123
	v_fma_f32 v122, -v122, v125, v124
	v_div_fmas_f32 v122, v122, v123, v125
	v_div_fixup_f32 v109, v122, v119, v47
	v_pk_mul_f32 v[34:35], v[108:109], v[34:35]
	v_cvt_pk_bf16_f32 v135, v34, v35
	global_store_dwordx4 v4, v[132:135], s[26:27]
	s_mov_b32 s50, 0
	s_add_i32 s12, s12, s22
	s_cmpk_lt_i32 s12, 0x100
	s_cbranch_scc0 .Lfm_nonext
	s_lshl_b32 s16, s12, 4
	s_add_i32 s16, s16, s91
	s_mul_i32 s17, s16, 0x2100
	s_add_u32 s24, s78, s17
	s_addc_u32 s25, s79, 0
	s_add_u32 s26, s24, 0x1900
	s_addc_u32 s27, s25, 0
	s_lshl_b32 s17, s16, 10
	s_add_u32 s28, s80, s17
	s_addc_u32 s29, s81, 0
	s_lshr_b32 s17, s16, 12
	s_lshl_b32 s17, s17, 11
	s_bfe_u32 s19, s16, 0x80004
	s_add_i32 s17, s17, s19
	s_mul_i32 s17, s17, 0x3180
	s_add_u32 s68, s86, s17
	s_addc_u32 s69, s87, 0
	s_and_b32 s19, s16, 15
	s_lshl_b32 s17, s19, 2
	s_addk_i32 s17, 0x3100
	s_add_u32 s30, s68, s17
	s_addc_u32 s31, s69, 0
	s_lshr_b32 s17, s19, 2
	s_lshl_b32 s17, s17, 7
	s_and_b32 s19, s19, 3
	s_lshl_b32 s19, s19, 1
	s_add_i32 s17, s17, s19
	s_addk_i32 s17, 0x2800
	s_add_u32 s70, s68, s17
	s_addc_u32 s71, s69, 0
	global_load_dword v24, v5, s[24:25] offset:3072
	global_load_dword v25, v5, s[24:25] offset:3104
	global_load_dword v26, v5, s[24:25] offset:3136
	global_load_dwordx4 v[28:31], v4, s[24:25] nt
	global_load_dwordx4 v[32:35], v4, s[24:25] offset:1024 nt
	global_load_dwordx4 v[36:39], v4, s[24:25] offset:2048 nt
	global_load_dwordx4 v[44:47], v4, s[26:27] offset:1024 nt
	global_load_dwordx4 v[48:51], v4, s[28:29] nt
	global_load_dwordx4 v[52:55], v4, s[26:27] nt
	global_load_dword v27, v6, s[30:31]
	global_load_ushort v56, v7, s[70:71] offset:0
	global_load_ushort v57, v7, s[70:71] offset:8
	global_load_ushort v58, v7, s[70:71] offset:16
	global_load_ushort v59, v7, s[70:71] offset:24
	global_load_ushort v60, v7, s[70:71] offset:32
	global_load_ushort v61, v7, s[70:71] offset:40
	global_load_ushort v62, v7, s[70:71] offset:48
	global_load_ushort v63, v7, s[70:71] offset:56
	s_waitcnt vmcnt(20)
	s_branch .Lfm_cb

.Lfm_cb:
	v_max3_f32 v127, v64, v65, v66
	v_sub_f32_e32 v102, v64, v127
	v_sub_f32_e32 v104, v65, v127
	v_sub_f32_e32 v106, v66, v127
	v_mul_f32_e32 v102, 0x3fb8aa3b, v102
	v_mul_f32_e32 v104, 0x3fb8aa3b, v104
	v_mul_f32_e32 v106, 0x3fb8aa3b, v106
	v_exp_f32_e32 v102, v102
	v_exp_f32_e32 v104, v104
	v_exp_f32_e32 v106, v106
	s_nop 0
	v_add_f32_e32 v127, v102, v104
	v_add_f32_e32 v127, v106, v127
	v_div_scale_f32 v122, s[72:73], v127, v127, 1.0
	v_rcp_f32_e32 v123, v122
	v_div_scale_f32 v124, vcc, 1.0, v127, 1.0
	v_fma_f32 v126, -v122, v123, 1.0
	v_fmac_f32_e32 v123, v126, v123
	v_mul_f32_e32 v125, v124, v123
	v_fma_f32 v126, -v122, v125, v124
	v_fmac_f32_e32 v125, v126, v123
	v_fma_f32 v122, -v122, v125, v124
	v_div_fmas_f32 v122, v122, v123, v125
	v_div_fixup_f32 v103, v122, v127, 1.0
	v_mul_f32_e32 v102, v102, v103
	v_mul_f32_e32 v104, v104, v103
	v_mul_f32_e32 v106, v106, v103
	v_lshlrev_b32_e32 v108, 16, v68
	v_and_b32_e32 v109, 0xffff0000, v68
	v_lshlrev_b32_e32 v110, 16, v72
	v_and_b32_e32 v111, 0xffff0000, v72
	v_lshlrev_b32_e32 v112, 16, v76
	v_and_b32_e32 v113, 0xffff0000, v76
	v_lshlrev_b32_e32 v114, 16, v80
	v_and_b32_e32 v115, 0xffff0000, v80
	v_pk_mul_f32 v[116:117], v[108:109], v[102:103] op_sel_hi:[1,0]
	v_pk_fma_f32 v[116:117], v[110:111], v[104:105], v[116:117] op_sel_hi:[1,0,1]
	v_pk_fma_f32 v[116:117], v[112:113], v[106:107], v[116:117] op_sel_hi:[1,0,1]
	v_pk_mul_f32 v[118:119], v[114:115], s[44:45]
	v_exp_f32_e32 v118, v118
	v_exp_f32_e32 v119, v119
	s_nop 0
	v_pk_add_f32 v[118:119], v[118:119], 1.0 op_sel_hi:[1,0]
	v_div_scale_f32 v122, s[72:73], v118, v118, v114
	v_rcp_f32_e32 v123, v122
	v_div_scale_f32 v124, vcc, v114, v118, v114
	v_fma_f32 v126, -v122, v123, 1.0
	v_fmac_f32_e32 v123, v126, v123
	v_mul_f32_e32 v125, v124, v123
	v_fma_f32 v126, -v122, v125, v124
	v_fmac_f32_e32 v125, v126, v123
	v_fma_f32 v122, -v122, v125, v124
	v_div_fmas_f32 v122, v122, v123, v125
	v_div_fixup_f32 v120, v122, v118, v114
	v_div_scale_f32 v122, s[72:73], v119, v119, v115
	v_rcp_f32_e32 v123, v122
	v_div_scale_f32 v124, vcc, v115, v119, v115
	v_fma_f32 v126, -v122, v123, 1.0
	v_fmac_f32_e32 v123, v126, v123
	v_mul_f32_e32 v125, v124, v123
	v_fma_f32 v126, -v122, v125, v124
	v_fmac_f32_e32 v125, v126, v123
	v_fma_f32 v122, -v122, v125, v124
	v_div_fmas_f32 v122, v122, v123, v125
	v_div_fixup_f32 v121, v122, v119, v115
	v_pk_mul_f32 v[116:117], v[120:121], v[116:117]
	v_cvt_pk_bf16_f32 v128, v116, v117
	v_lshlrev_b32_e32 v108, 16, v69
	v_and_b32_e32 v109, 0xffff0000, v69
	v_lshlrev_b32_e32 v110, 16, v73
	v_and_b32_e32 v111, 0xffff0000, v73
	v_lshlrev_b32_e32 v112, 16, v77
	v_and_b32_e32 v113, 0xffff0000, v77
	v_lshlrev_b32_e32 v114, 16, v81
	v_and_b32_e32 v115, 0xffff0000, v81
	v_pk_mul_f32 v[116:117], v[108:109], v[102:103] op_sel_hi:[1,0]
	v_pk_fma_f32 v[116:117], v[110:111], v[104:105], v[116:117] op_sel_hi:[1,0,1]
	v_pk_fma_f32 v[116:117], v[112:113], v[106:107], v[116:117] op_sel_hi:[1,0,1]
	v_pk_mul_f32 v[118:119], v[114:115], s[44:45]
	v_exp_f32_e32 v118, v118
	v_exp_f32_e32 v119, v119
	s_nop 0
	v_pk_add_f32 v[118:119], v[118:119], 1.0 op_sel_hi:[1,0]
	v_div_scale_f32 v122, s[72:73], v118, v118, v114
	v_rcp_f32_e32 v123, v122
	v_div_scale_f32 v124, vcc, v114, v118, v114
	v_fma_f32 v126, -v122, v123, 1.0
	v_fmac_f32_e32 v123, v126, v123
	v_mul_f32_e32 v125, v124, v123
	v_fma_f32 v126, -v122, v125, v124
	v_fmac_f32_e32 v125, v126, v123
	v_fma_f32 v122, -v122, v125, v124
	v_div_fmas_f32 v122, v122, v123, v125
	v_div_fixup_f32 v120, v122, v118, v114
	v_div_scale_f32 v122, s[72:73], v119, v119, v115
	v_rcp_f32_e32 v123, v122
	v_div_scale_f32 v124, vcc, v115, v119, v115
	v_fma_f32 v126, -v122, v123, 1.0
	v_fmac_f32_e32 v123, v126, v123
	v_mul_f32_e32 v125, v124, v123
	v_fma_f32 v126, -v122, v125, v124
	v_fmac_f32_e32 v125, v126, v123
	v_fma_f32 v122, -v122, v125, v124
	v_div_fmas_f32 v122, v122, v123, v125
	v_div_fixup_f32 v121, v122, v119, v115
	v_pk_mul_f32 v[116:117], v[120:121], v[116:117]
	v_cvt_pk_bf16_f32 v129, v116, v117
	v_lshlrev_b32_e32 v108, 16, v70
	v_and_b32_e32 v109, 0xffff0000, v70
	v_lshlrev_b32_e32 v110, 16, v74
	v_and_b32_e32 v111, 0xffff0000, v74
	v_lshlrev_b32_e32 v112, 16, v78
	v_and_b32_e32 v113, 0xffff0000, v78
	v_lshlrev_b32_e32 v114, 16, v82
	v_and_b32_e32 v115, 0xffff0000, v82
	v_pk_mul_f32 v[116:117], v[108:109], v[102:103] op_sel_hi:[1,0]
	v_pk_fma_f32 v[116:117], v[110:111], v[104:105], v[116:117] op_sel_hi:[1,0,1]
	v_pk_fma_f32 v[116:117], v[112:113], v[106:107], v[116:117] op_sel_hi:[1,0,1]
	v_pk_mul_f32 v[118:119], v[114:115], s[44:45]
	v_exp_f32_e32 v118, v118
	v_exp_f32_e32 v119, v119
	s_nop 0
	v_pk_add_f32 v[118:119], v[118:119], 1.0 op_sel_hi:[1,0]
	v_div_scale_f32 v122, s[72:73], v118, v118, v114
	v_rcp_f32_e32 v123, v122
	v_div_scale_f32 v124, vcc, v114, v118, v114
	v_fma_f32 v126, -v122, v123, 1.0
	v_fmac_f32_e32 v123, v126, v123
	v_mul_f32_e32 v125, v124, v123
	v_fma_f32 v126, -v122, v125, v124
	v_fmac_f32_e32 v125, v126, v123
	v_fma_f32 v122, -v122, v125, v124
	v_div_fmas_f32 v122, v122, v123, v125
	v_div_fixup_f32 v120, v122, v118, v114
	v_div_scale_f32 v122, s[72:73], v119, v119, v115
	v_rcp_f32_e32 v123, v122
	v_div_scale_f32 v124, vcc, v115, v119, v115
	v_fma_f32 v126, -v122, v123, 1.0
	v_fmac_f32_e32 v123, v126, v123
	v_mul_f32_e32 v125, v124, v123
	v_fma_f32 v126, -v122, v125, v124
	v_fmac_f32_e32 v125, v126, v123
	v_fma_f32 v122, -v122, v125, v124
	v_div_fmas_f32 v122, v122, v123, v125
	v_div_fixup_f32 v121, v122, v119, v115
	v_pk_mul_f32 v[116:117], v[120:121], v[116:117]
	v_cvt_pk_bf16_f32 v130, v116, v117
	v_lshlrev_b32_e32 v108, 16, v71
	v_and_b32_e32 v109, 0xffff0000, v71
	v_lshlrev_b32_e32 v110, 16, v75
	v_and_b32_e32 v111, 0xffff0000, v75
	v_lshlrev_b32_e32 v112, 16, v79
	v_and_b32_e32 v113, 0xffff0000, v79
	v_lshlrev_b32_e32 v114, 16, v83
	v_and_b32_e32 v115, 0xffff0000, v83
	v_pk_mul_f32 v[116:117], v[108:109], v[102:103] op_sel_hi:[1,0]
	v_pk_fma_f32 v[116:117], v[110:111], v[104:105], v[116:117] op_sel_hi:[1,0,1]
	v_pk_fma_f32 v[116:117], v[112:113], v[106:107], v[116:117] op_sel_hi:[1,0,1]
	v_pk_mul_f32 v[118:119], v[114:115], s[44:45]
	v_exp_f32_e32 v118, v118
	v_exp_f32_e32 v119, v119
	s_nop 0
	v_pk_add_f32 v[118:119], v[118:119], 1.0 op_sel_hi:[1,0]
	v_div_scale_f32 v122, s[72:73], v118, v118, v114
	v_rcp_f32_e32 v123, v122
	v_div_scale_f32 v124, vcc, v114, v118, v114
	v_fma_f32 v126, -v122, v123, 1.0
	v_fmac_f32_e32 v123, v126, v123
	v_mul_f32_e32 v125, v124, v123
	v_fma_f32 v126, -v122, v125, v124
	v_fmac_f32_e32 v125, v126, v123
	v_fma_f32 v122, -v122, v125, v124
	v_div_fmas_f32 v122, v122, v123, v125
	v_div_fixup_f32 v120, v122, v118, v114
	v_div_scale_f32 v122, s[72:73], v119, v119, v115
	v_rcp_f32_e32 v123, v122
	v_div_scale_f32 v124, vcc, v115, v119, v115
	v_fma_f32 v126, -v122, v123, 1.0
	v_fmac_f32_e32 v123, v126, v123
	v_mul_f32_e32 v125, v124, v123
	v_fma_f32 v126, -v122, v125, v124
	v_fmac_f32_e32 v125, v126, v123
	v_fma_f32 v122, -v122, v125, v124
	v_div_fmas_f32 v122, v122, v123, v125
	v_div_fixup_f32 v121, v122, v119, v115
	v_pk_mul_f32 v[116:117], v[120:121], v[116:117]
	v_cvt_pk_bf16_f32 v131, v116, v117
	global_store_dwordx4 v4, v[128:131], s[60:61] offset:1024
	v_lshlrev_b32_e32 v68, 16, v84
	v_and_b32_e32 v69, 0xffff0000, v84
	v_lshlrev_b32_e32 v70, 16, v85
	v_and_b32_e32 v71, 0xffff0000, v85
	v_lshlrev_b32_e32 v72, 16, v86
	v_and_b32_e32 v73, 0xffff0000, v86
	v_lshlrev_b32_e32 v74, 16, v87
	v_and_b32_e32 v75, 0xffff0000, v87
	v_lshlrev_b32_e32 v76, 16, v88
	v_and_b32_e32 v77, 0xffff0000, v88
	v_lshlrev_b32_e32 v78, 16, v89
	v_and_b32_e32 v79, 0xffff0000, v89
	v_lshlrev_b32_e32 v80, 16, v90
	v_and_b32_e32 v81, 0xffff0000, v90
	v_lshlrev_b32_e32 v82, 16, v91
	v_and_b32_e32 v83, 0xffff0000, v91
	v_lshlrev_b32_e32 v92, 16, v92
	v_lshlrev_b32_e32 v93, 16, v93
	v_lshlrev_b32_e32 v94, 16, v94
	v_lshlrev_b32_e32 v95, 16, v95
	v_lshlrev_b32_e32 v96, 16, v96
	v_lshlrev_b32_e32 v97, 16, v97
	v_lshlrev_b32_e32 v98, 16, v98
	v_lshlrev_b32_e32 v99, 16, v99
	v_add_f32_e32 v108, v68, v69
	v_add_f32_e32 v108, v108, v70
	v_add_f32_e32 v108, v108, v71
	v_add_f32_e32 v108, v108, v72
	v_add_f32_e32 v108, v108, v73
	v_add_f32_e32 v108, v108, v74
	v_add_f32_e32 v108, v108, v75
	s_nop 1
	v_add_f32_dpp v109, v108, v108 quad_perm:[1,0,3,2] row_mask:0xf bank_mask:0xf
	s_nop 1
	v_add_f32_dpp v108, v109, v109 quad_perm:[2,3,0,1] row_mask:0xf bank_mask:0xf
	s_nop 1
	v_add_f32_dpp v109, v108, v108 row_half_mirror row_mask:0xf bank_mask:0xf
	v_mov_b32_e32 v108, v109
	v_mul_f32_e32 v108, 0x3c800000, v108
	v_pk_add_f32 v[68:69], v[68:69], v[108:109] op_sel_hi:[1,0] neg_lo:[0,1] neg_hi:[0,1]
	v_pk_add_f32 v[70:71], v[70:71], v[108:109] op_sel_hi:[1,0] neg_lo:[0,1] neg_hi:[0,1]
	v_pk_add_f32 v[72:73], v[72:73], v[108:109] op_sel_hi:[1,0] neg_lo:[0,1] neg_hi:[0,1]
	v_pk_add_f32 v[74:75], v[74:75], v[108:109] op_sel_hi:[1,0] neg_lo:[0,1] neg_hi:[0,1]
	v_pk_mul_f32 v[110:111], v[68:69], v[68:69]
	v_pk_mul_f32 v[112:113], v[70:71], v[70:71]
	v_pk_mul_f32 v[114:115], v[72:73], v[72:73]
	v_pk_mul_f32 v[116:117], v[74:75], v[74:75]
	v_add_f32_e32 v118, v110, v111
	v_add_f32_e32 v118, v112, v118
	v_add_f32_e32 v118, v113, v118
	v_add_f32_e32 v118, v114, v118
	v_add_f32_e32 v118, v115, v118
	v_add_f32_e32 v118, v116, v118
	v_add_f32_e32 v118, v117, v118
	s_nop 1
	v_add_f32_dpp v119, v118, v118 quad_perm:[1,0,3,2] row_mask:0xf bank_mask:0xf
	s_nop 1
	v_add_f32_dpp v118, v119, v119 quad_perm:[2,3,0,1] row_mask:0xf bank_mask:0xf
	s_nop 1
	v_add_f32_dpp v119, v118, v118 row_half_mirror row_mask:0xf bank_mask:0xf
	v_mov_b32_e32 v118, v119
	v_fmamk_f32 v118, v118, 0x3c800000, v100
	v_rsq_f32_e32 v118, v118
	v_mov_b32_e32 v120, v67
	v_pk_mul_f32 v[68:69], v[68:69], v[118:119] op_sel_hi:[1,0]
	v_pk_mul_f32 v[70:71], v[70:71], v[118:119] op_sel_hi:[1,0]
	v_pk_mul_f32 v[72:73], v[72:73], v[118:119] op_sel_hi:[1,0]
	v_pk_mul_f32 v[74:75], v[74:75], v[118:119] op_sel_hi:[1,0]
	v_pk_fma_f32 v[68:69], v[8:9], v[68:69], v[16:17]
	v_pk_fma_f32 v[70:71], v[10:11], v[70:71], v[18:19]
	v_pk_fma_f32 v[72:73], v[12:13], v[72:73], v[20:21]
	v_pk_fma_f32 v[74:75], v[14:15], v[74:75], v[22:23]
	v_pk_fma_f32 v[68:69], v[120:121], v[92:93], v[68:69] op_sel_hi:[0,1,1]
	v_pk_fma_f32 v[70:71], v[120:121], v[94:95], v[70:71] op_sel_hi:[0,1,1]
	v_pk_fma_f32 v[72:73], v[120:121], v[96:97], v[72:73] op_sel_hi:[0,1,1]
	v_pk_fma_f32 v[74:75], v[120:121], v[98:99], v[74:75] op_sel_hi:[0,1,1]
	v_pk_mul_f32 v[118:119], v[76:77], s[44:45]
	v_exp_f32_e32 v118, v118
	v_exp_f32_e32 v119, v119
	s_nop 0
	v_pk_add_f32 v[118:119], v[118:119], 1.0 op_sel_hi:[1,0]
	v_div_scale_f32 v122, s[72:73], v118, v118, v76
	v_rcp_f32_e32 v123, v122
	v_div_scale_f32 v124, vcc, v76, v118, v76
	v_fma_f32 v126, -v122, v123, 1.0
	v_fmac_f32_e32 v123, v126, v123
	v_mul_f32_e32 v125, v124, v123
	v_fma_f32 v126, -v122, v125, v124
	v_fmac_f32_e32 v125, v126, v123
	v_fma_f32 v122, -v122, v125, v124
	v_div_fmas_f32 v122, v122, v123, v125
	v_div_fixup_f32 v108, v122, v118, v76
	v_div_scale_f32 v122, s[72:73], v119, v119, v77
	v_rcp_f32_e32 v123, v122
	v_div_scale_f32 v124, vcc, v77, v119, v77
	v_fma_f32 v126, -v122, v123, 1.0
	v_fmac_f32_e32 v123, v126, v123
	v_mul_f32_e32 v125, v124, v123
	v_fma_f32 v126, -v122, v125, v124
	v_fmac_f32_e32 v125, v126, v123
	v_fma_f32 v122, -v122, v125, v124
	v_div_fmas_f32 v122, v122, v123, v125
	v_div_fixup_f32 v109, v122, v119, v77
	v_pk_mul_f32 v[68:69], v[108:109], v[68:69]
	v_cvt_pk_bf16_f32 v132, v68, v69
	v_pk_mul_f32 v[118:119], v[78:79], s[44:45]
	v_exp_f32_e32 v118, v118
	v_exp_f32_e32 v119, v119
	s_nop 0
	v_pk_add_f32 v[118:119], v[118:119], 1.0 op_sel_hi:[1,0]
	v_div_scale_f32 v122, s[72:73], v118, v118, v78
	v_rcp_f32_e32 v123, v122
	v_div_scale_f32 v124, vcc, v78, v118, v78
	v_fma_f32 v126, -v122, v123, 1.0
	v_fmac_f32_e32 v123, v126, v123
	v_mul_f32_e32 v125, v124, v123
	v_fma_f32 v126, -v122, v125, v124
	v_fmac_f32_e32 v125, v126, v123
	v_fma_f32 v122, -v122, v125, v124
	v_div_fmas_f32 v122, v122, v123, v125
	v_div_fixup_f32 v108, v122, v118, v78
	v_div_scale_f32 v122, s[72:73], v119, v119, v79
	v_rcp_f32_e32 v123, v122
	v_div_scale_f32 v124, vcc, v79, v119, v79
	v_fma_f32 v126, -v122, v123, 1.0
	v_fmac_f32_e32 v123, v126, v123
	v_mul_f32_e32 v125, v124, v123
	v_fma_f32 v126, -v122, v125, v124
	v_fmac_f32_e32 v125, v126, v123
	v_fma_f32 v122, -v122, v125, v124
	v_div_fmas_f32 v122, v122, v123, v125
	v_div_fixup_f32 v109, v122, v119, v79
	v_pk_mul_f32 v[70:71], v[108:109], v[70:71]
	v_cvt_pk_bf16_f32 v133, v70, v71
	v_pk_mul_f32 v[118:119], v[80:81], s[44:45]
	v_exp_f32_e32 v118, v118
	v_exp_f32_e32 v119, v119
	s_nop 0
	v_pk_add_f32 v[118:119], v[118:119], 1.0 op_sel_hi:[1,0]
	v_div_scale_f32 v122, s[72:73], v118, v118, v80
	v_rcp_f32_e32 v123, v122
	v_div_scale_f32 v124, vcc, v80, v118, v80
	v_fma_f32 v126, -v122, v123, 1.0
	v_fmac_f32_e32 v123, v126, v123
	v_mul_f32_e32 v125, v124, v123
	v_fma_f32 v126, -v122, v125, v124
	v_fmac_f32_e32 v125, v126, v123
	v_fma_f32 v122, -v122, v125, v124
	v_div_fmas_f32 v122, v122, v123, v125
	v_div_fixup_f32 v108, v122, v118, v80
	v_div_scale_f32 v122, s[72:73], v119, v119, v81
	v_rcp_f32_e32 v123, v122
	v_div_scale_f32 v124, vcc, v81, v119, v81
	v_fma_f32 v126, -v122, v123, 1.0
	v_fmac_f32_e32 v123, v126, v123
	v_mul_f32_e32 v125, v124, v123
	v_fma_f32 v126, -v122, v125, v124
	v_fmac_f32_e32 v125, v126, v123
	v_fma_f32 v122, -v122, v125, v124
	v_div_fmas_f32 v122, v122, v123, v125
	v_div_fixup_f32 v109, v122, v119, v81
	v_pk_mul_f32 v[72:73], v[108:109], v[72:73]
	v_cvt_pk_bf16_f32 v134, v72, v73
	v_pk_mul_f32 v[118:119], v[82:83], s[44:45]
	v_exp_f32_e32 v118, v118
	v_exp_f32_e32 v119, v119
	s_nop 0
	v_pk_add_f32 v[118:119], v[118:119], 1.0 op_sel_hi:[1,0]
	v_div_scale_f32 v122, s[72:73], v118, v118, v82
	v_rcp_f32_e32 v123, v122
	v_div_scale_f32 v124, vcc, v82, v118, v82
	v_fma_f32 v126, -v122, v123, 1.0
	v_fmac_f32_e32 v123, v126, v123
	v_mul_f32_e32 v125, v124, v123
	v_fma_f32 v126, -v122, v125, v124
	v_fmac_f32_e32 v125, v126, v123
	v_fma_f32 v122, -v122, v125, v124
	v_div_fmas_f32 v122, v122, v123, v125
	v_div_fixup_f32 v108, v122, v118, v82
	v_div_scale_f32 v122, s[72:73], v119, v119, v83
	v_rcp_f32_e32 v123, v122
	v_div_scale_f32 v124, vcc, v83, v119, v83
	v_fma_f32 v126, -v122, v123, 1.0
	v_fmac_f32_e32 v123, v126, v123
	v_mul_f32_e32 v125, v124, v123
	v_fma_f32 v126, -v122, v125, v124
	v_fmac_f32_e32 v125, v126, v123
	v_fma_f32 v122, -v122, v125, v124
	v_div_fmas_f32 v122, v122, v123, v125
	v_div_fixup_f32 v109, v122, v119, v83
	v_pk_mul_f32 v[74:75], v[108:109], v[74:75]
	v_cvt_pk_bf16_f32 v135, v74, v75
	global_store_dwordx4 v4, v[132:135], s[60:61]
	s_cmpk_lt_i32 s12, 0x100
	s_cbranch_scc1 .Lfm_loop
